# P2 queue: up-projection tiles first, then the top-k jobs batch by batch (phase ends on the shortest top-k jobs)
# speedup vs baseline: 1.0051x; 1.0051x over previous
; __global__ void __launch_bounds__(NTHREADS) mega(Params p) {
;     ...
;       constexpr int NTK = 2 * 2052, NUP = 66 * 14, NJ = NTK + NUP + 16;
;       int pending = 0, par = 0;
;       if (threadIdx.x == 0) pending = (int)atomicAdd(p.ctr + l * 2 + 8 * rep, 1u);
;       for (;;) {
;         const int j = next_job(p.ctr + l * 2 + 8 * rep, lds, pending, NJ, par);
;         if (j >= NJ) break;
;         if (j < 16) {
;           cumsum_job(p, j, lds);
;         } else if (j < 16 + NTK) {
;           const int jj = j - 16;
;           const int b = jj & 1, q = 2051 - (jj >> 1);
;           topk_job(p, b, LEAD + 4 * q, lds);
;         } else {
;           const int u = j - 16 - NTK;
;           upproj_tile(p, u / 14, u % 14, lds);
;         }
.LBB0_618:
	s_sub_i32 s2, s87, 16
	s_cmpk_lt_u32 s2, 0x13a4
	s_cbranch_scc0 .Ltks_a
	s_cmpk_lt_u32 s2, 0x39c
	s_cbranch_scc0 .Ltkm_a
	s_add_i32 s87, s2, 0x1018
	s_branch .Ltks_a
.Ltkm_a:
	s_sub_i32 s2, s2, 0x39c
	s_cmpk_lt_u32 s2, 0x804
	s_cselect_b32 s3, 0, 1
	s_cbranch_scc1 .Ltkb_a
	s_sub_i32 s2, s2, 0x804

; DI int next_job(unsigned* ctr, char* lds, int& pending, int njobs, int& par) {
;   int* sj = (int*)(lds + LDS_JOB);
;   if (threadIdx.x == 0) sj[par] = pending;
;   __syncthreads();
;   const int j = sj[par];
;   par ^= 1;
;   if (threadIdx.x == 0 && j < njobs) pending = (int)atomicAdd(ctr, 1u);
;   return j;
; __global__ void __launch_bounds__(NTHREADS) mega(Params p) {
;     ...
;         const int j = next_job(p.ctr + l * 2 + 8 * rep, lds, pending, NJ, par);
;         if (j >= NJ) break;
;         if (j < 16) {
;           cumsum_job(p, j, lds);
;         } else if (j < 16 + NTK) {
;           const int jj = j - 16;
;           const int b = jj & 1, q = 2051 - (jj >> 1);
;           topk_job(p, b, LEAD + 4 * q, lds);
;         } else {
;           const int u = j - 16 - NTK;
;           upproj_tile(p, u / 14, u % 14, lds);
;         }
.Lsc_end:
	s_waitcnt vmcnt(0) lgkmcnt(0)
	v_lshrrev_b32_e32 v0, 6, v100
	s_mov_b32 s3, s90
	v_readfirstlane_b32 s2, v0
	s_lshl_b32 s4, s87, 1
	s_and_b32 s4, s4, 0x3ffc
	s_sub_i32 s4, 0x209c, s4
	s_bitcmp1_b32 s87, 0
	s_cselect_b32 s5, 0x2100, 0
	s_add_i32 s4, s4, s5
	v_readlane_b32 s6, v240, 13
	v_readlane_b32 s7, v240, 14
	s_lshl_b32 s5, s4, 9
	s_add_u32 s40, s6, s5
	s_addc_u32 s41, s7, 0
	s_add_u32 s42, s40, 0x200
	s_addc_u32 s43, s41, 0
	s_add_u32 s44, s42, 0x200
	s_addc_u32 s45, s43, 0
	s_add_u32 s46, s44, 0x200
	s_addc_u32 s47, s45, 0
	s_mov_b32 s16, 0x55555555
	s_mov_b32 s17, 0x55555555
	s_mov_b32 s18, 0x33333333
	s_mov_b32 s19, 0x33333333
	s_mov_b32 s20, 0xf0f0f0f
	s_mov_b32 s21, 0xf0f0f0f
	s_mov_b32 s22, 0xff00ff
	s_mov_b32 s23, 0xff00ff
	s_mov_b32 s24, 0xffff
	s_mov_b32 s25, 0xffff
	s_mov_b32 s26, 0xffffffff
	s_mov_b32 s27, 0
	v_mov_b32_e32 v20, 1
	v_and_b32_e32 v0, 3, v101
	v_lshlrev_b32_e32 v0, 12, v0
	v_add_u32_e32 v21, 0x4000, v0
	v_add_u32_e32 v25, 0x14000, v0
	v_mov_b32_e32 v29, 0x4000
	v_add_u32_e32 v22, 0x8000, v0
	v_add_u32_e32 v26, 0x18000, v0
	v_mov_b32_e32 v30, 0x8000
	v_add_u32_e32 v23, 0xc000, v0
	v_add_u32_e32 v27, 0x1c000, v0
	v_mov_b32_e32 v31, 0xc000
	v_add_u32_e32 v24, 0x10000, v0
	v_add_u32_e32 v28, 0x20000, v0
	v_mov_b32_e32 v32, 0x10000
	s_movk_i32 s85, 0x100
	s_mov_b32 s56, 0
	s_mov_b32 s58, 0
	v_cmp_eq_u32_e32 vcc, 0, v100
	s_and_saveexec_b64 s[30:31], vcc
	ds_write_b32 v3, v136 offset:768
	s_mov_b64 exec, s[30:31]
	s_waitcnt lgkmcnt(0)
	v_lshlrev_b32_e32 v75, 2, v100
	v_add_u32_e32 v75, 0x2800, v75
	v_lshlrev_b32_e32 v76, 1, v100
	v_add_u32_e32 v76, 0x800, v76
	s_barrier
	v_mov_b32_e32 v4, 0
	v_mov_b32_e32 v5, 0
	v_mov_b32_e32 v6, 0
	v_mov_b32_e32 v7, 0
	v_lshlrev_b32_e32 v0, 4, v100
	v_add_u32_e32 v0, 0x4000, v0
	v_add_u32_e32 v1, 0x10000, v0
	ds_write_b128 v0, v[4:7]
	ds_write_b128 v0, v[4:7] offset:8192
	ds_write_b128 v0, v[4:7] offset:16384
	ds_write_b128 v0, v[4:7] offset:24576
	ds_write_b128 v0, v[4:7] offset:32768
	ds_write_b128 v0, v[4:7] offset:40960
	ds_write_b128 v0, v[4:7] offset:49152
	ds_write_b128 v0, v[4:7] offset:57344
	v_mov_b32_e32 v2, -1
	v_lshlrev_b32_e32 v0, 2, v100
	ds_write_b32 v0, v2 offset:8192
	s_waitcnt lgkmcnt(0)
	s_barrier
	ds_read_b32 v0, v3 offset:768
	s_waitcnt lgkmcnt(0)
	v_readfirstlane_b32 s63, v0
	s_sub_i32 s4, s63, 16
	s_cmpk_lt_u32 s4, 0x13a4
	s_cbranch_scc0 .Ltks_b
	s_cmpk_lt_u32 s4, 0x39c
	s_cbranch_scc0 .Ltkm_b
	s_add_i32 s63, s4, 0x1018
	s_branch .Ltks_b
.Ltkm_b:
	s_sub_i32 s4, s4, 0x39c
	s_cmpk_lt_u32 s4, 0x804
	s_cselect_b32 s5, 0, 1
	s_cbranch_scc1 .Ltkb_b
	s_sub_i32 s4, s4, 0x804
